# pool_pass: two items of a thread loaded together; attention second-half staging wait counted (vmcnt(3) when the next-tile loads were issued)
# speedup vs baseline: 1.0028x; 1.0002x over previous
.LBB0_250:
	s_add_i32 s11, s10, 1
	s_cmp_lg_u32 s10, 2
	s_cselect_b32 s10, s11, 0
	s_mul_i32 s11, s10, 0x3400
	s_waitcnt vmcnt(3)
	v_lshl_add_u32 v64, s10, 13, v179
	s_add_i32 s11, s11, 0
	s_and_b64 vcc, exec, s[54:55]
	s_cbranch_vccz .Lattn_w3
	s_waitcnt vmcnt(0)
.Lattn_w3:
	ds_write_b128 v64, v[132:135]
	v_add_u32_e32 v64, s11, v148
	ds_write_b128 v64, v[128:131] offset:24576
	v_add_u32_e32 v64, s11, v149
	v_cmp_gt_f32_e32 vcc, 1.0, v176
	ds_write_b64 v64, v[172:173] offset:24576
	s_cbranch_vccz .LBB0_252
	v_pk_mul_f32 v[14:15], v[14:15], v[176:177] op_sel_hi:[1,0]
	v_pk_mul_f32 v[12:13], v[12:13], v[176:177] op_sel_hi:[1,0]
	v_pk_mul_f32 v[10:11], v[10:11], v[176:177] op_sel_hi:[1,0]
	v_pk_mul_f32 v[8:9], v[8:9], v[176:177] op_sel_hi:[1,0]
	v_pk_mul_f32 v[6:7], v[6:7], v[176:177] op_sel_hi:[1,0]
	v_pk_mul_f32 v[4:5], v[4:5], v[176:177] op_sel_hi:[1,0]
	v_pk_mul_f32 v[2:3], v[2:3], v[176:177] op_sel_hi:[1,0]
	v_pk_mul_f32 v[0:1], v[0:1], v[176:177] op_sel_hi:[1,0]
	v_pk_mul_f32 v[46:47], v[46:47], v[176:177] op_sel_hi:[1,0]
	v_pk_mul_f32 v[44:45], v[44:45], v[176:177] op_sel_hi:[1,0]
	v_pk_mul_f32 v[42:43], v[42:43], v[176:177] op_sel_hi:[1,0]
	v_pk_mul_f32 v[40:41], v[40:41], v[176:177] op_sel_hi:[1,0]
	v_pk_mul_f32 v[38:39], v[38:39], v[176:177] op_sel_hi:[1,0]
	v_pk_mul_f32 v[36:37], v[36:37], v[176:177] op_sel_hi:[1,0]
	v_pk_mul_f32 v[34:35], v[34:35], v[176:177] op_sel_hi:[1,0]
	v_pk_mul_f32 v[32:33], v[32:33], v[176:177] op_sel_hi:[1,0]

.LBB0_302:
	v_ashrrev_i32_e32 v16, 5, v14
	s_nop 0
	v_readfirstlane_b32 s4, v16
	s_and_b32 s4, s4, 0xfff
	s_cmp_lt_u32 s4, 16
	s_cbranch_scc1 .Lpool_slow
	s_cmpk_gt_u32 s4, 0xfee
	s_cbranch_scc1 .Lpool_slow
	s_add_u32 s6, s50, 0x6a00000
	s_addc_u32 s7, s51, 0
	v_sub_u32_e32 v112, v16, v15
	v_mul_u32_u24_e32 v112, 0x1800, v112
	v_add_u32_e32 v112, v112, v168
	v_mul_u32_u24_e32 v122, 0x1800, v16
	v_add_u32_e32 v122, v122, v168
	s_cmpk_lg_i32 s31, 0x100
	s_cbranch_scc1 .Lpool_single
	v_readfirstlane_b32 s5, v14
	s_add_i32 s5, s5, s0
	s_cmp_gt_i32 s5, s21
	s_cbranch_scc1 .Lpool_single
	s_add_u32 s42, s6, 0x1800000
	s_addc_u32 s43, s7, 0
	global_load_dwordx4 v[40:43], v112, s[6:7]
	v_add_u32_e32 v113, 0x1800, v112
	global_load_dwordx4 v[44:47], v113, s[6:7]
	global_load_dwordx4 v[128:131], v112, s[42:43]
	v_add_u32_e32 v113, 0x1800, v112
	global_load_dwordx4 v[132:135], v113, s[42:43]
	s_mov_b64 s[10:11], exec
	s_mov_b32 s8, 0xffffff00
	s_mov_b32 s9, 0xffffff00
	s_mov_b64 exec, s[8:9]
	v_add_u32_e32 v113, 0x3000, v112
	global_load_dwordx4 v[48:51], v113, s[6:7]
	v_add_u32_e32 v113, 0x4800, v112
	global_load_dwordx4 v[52:55], v113, s[6:7]
	v_add_u32_e32 v113, 0x3000, v112
	global_load_dwordx4 v[136:139], v113, s[42:43]
	v_add_u32_e32 v113, 0x4800, v112
	global_load_dwordx4 v[140:143], v113, s[42:43]
	s_mov_b32 s8, 0xffff0000
	s_mov_b32 s9, 0xffff0000
	s_mov_b64 exec, s[8:9]
	v_add_u32_e32 v113, 0x6000, v112
	global_load_dwordx4 v[56:59], v113, s[6:7]
	v_add_u32_e32 v113, 0x7800, v112
	global_load_dwordx4 v[60:63], v113, s[6:7]
	v_add_u32_e32 v113, 0x9000, v112
	global_load_dwordx4 v[64:67], v113, s[6:7]
	v_add_u32_e32 v113, 0xa800, v112
	global_load_dwordx4 v[68:71], v113, s[6:7]
	v_add_u32_e32 v113, 0x6000, v112
	global_load_dwordx4 v[144:147], v113, s[42:43]
	v_add_u32_e32 v113, 0x7800, v112
	global_load_dwordx4 v[148:151], v113, s[42:43]
	v_add_u32_e32 v113, 0x9000, v112
	global_load_dwordx4 v[152:155], v113, s[42:43]
	v_add_u32_e32 v113, 0xa800, v112
	global_load_dwordx4 v[156:159], v113, s[42:43]
	s_mov_b32 s8, 0xff000000
	s_mov_b32 s9, 0xff000000
	s_mov_b64 exec, s[8:9]
	v_add_u32_e32 v113, 0xc000, v112
	global_load_dwordx4 v[72:75], v113, s[6:7]
	v_add_u32_e32 v113, 0xd800, v112
	global_load_dwordx4 v[76:79], v113, s[6:7]
	v_add_u32_e32 v113, 0xf000, v112
	global_load_dwordx4 v[80:83], v113, s[6:7]
	v_add_u32_e32 v113, 0x10800, v112
	global_load_dwordx4 v[84:87], v113, s[6:7]
	v_add_u32_e32 v113, 0x12000, v112
	global_load_dwordx4 v[88:91], v113, s[6:7]
	v_add_u32_e32 v113, 0x13800, v112
	global_load_dwordx4 v[92:95], v113, s[6:7]
	v_add_u32_e32 v113, 0x15000, v112
	global_load_dwordx4 v[96:99], v113, s[6:7]
	v_add_u32_e32 v113, 0x16800, v112
	global_load_dwordx4 v[100:103], v113, s[6:7]
	v_add_u32_e32 v113, 0xc000, v112
	global_load_dwordx4 v[160:163], v113, s[42:43]
	v_add_u32_e32 v113, 0xd800, v112
	global_load_dwordx4 v[164:167], v113, s[42:43]
	v_add_u32_e32 v113, 0xf000, v112
	global_load_dwordx4 v[172:175], v113, s[42:43]
	v_add_u32_e32 v113, 0x10800, v112
	global_load_dwordx4 v[176:179], v113, s[42:43]
	v_add_u32_e32 v113, 0x12000, v112
	global_load_dwordx4 v[180:183], v113, s[42:43]
	v_add_u32_e32 v113, 0x13800, v112
	global_load_dwordx4 v[184:187], v113, s[42:43]
	v_add_u32_e32 v113, 0x15000, v112
	global_load_dwordx4 v[188:191], v113, s[42:43]
	v_add_u32_e32 v113, 0x16800, v112
	global_load_dwordx4 v[192:195], v113, s[42:43]
	s_mov_b64 exec, s[10:11]
	global_load_dwordx4 v[104:107], v122, s[6:7]
	global_load_dwordx4 v[108:111], v122, s[6:7] offset:3584
	global_load_dwordx4 v[208:211], v122, s[42:43]
	global_load_dwordx4 v[212:215], v122, s[42:43] offset:3584
	v_mov_b32_e32 v114, 0
	v_mov_b32_e32 v115, 0
	v_mov_b32_e32 v116, 0
	v_mov_b32_e32 v117, 0
	v_mov_b32_e32 v118, 0
	v_mov_b32_e32 v119, 0
	v_mov_b32_e32 v120, 0
	v_mov_b32_e32 v121, 0
	v_mov_b32_e32 v216, 0
	v_mov_b32_e32 v217, 0
	v_mov_b32_e32 v218, 0
	v_mov_b32_e32 v219, 0
	v_mov_b32_e32 v220, 0
	v_mov_b32_e32 v221, 0
	v_mov_b32_e32 v222, 0
	v_mov_b32_e32 v223, 0
	v_bfe_u32 v123, v207, 3, 2
	v_sub_u32_e32 v123, 0x7e, v123
	v_lshlrev_b32_e32 v123, 23, v123
	s_waitcnt vmcnt(34)
	v_lshlrev_b32_e32 v124, 16, v40
	v_and_b32_e32 v125, 0xffff0000, v40
	v_add_f32_e32 v114, v114, v124
	v_add_f32_e32 v115, v115, v125
	v_lshlrev_b32_e32 v124, 16, v41
	v_and_b32_e32 v125, 0xffff0000, v41
	v_add_f32_e32 v116, v116, v124
	v_add_f32_e32 v117, v117, v125
	v_lshlrev_b32_e32 v124, 16, v42
	v_and_b32_e32 v125, 0xffff0000, v42
	v_add_f32_e32 v118, v118, v124
	v_add_f32_e32 v119, v119, v125
	v_lshlrev_b32_e32 v124, 16, v43
	v_and_b32_e32 v125, 0xffff0000, v43
	v_add_f32_e32 v120, v120, v124
	v_add_f32_e32 v121, v121, v125
	v_lshlrev_b32_e32 v124, 16, v44
	v_and_b32_e32 v125, 0xffff0000, v44
	v_add_f32_e32 v114, v114, v124
	v_add_f32_e32 v115, v115, v125
	v_lshlrev_b32_e32 v124, 16, v45
	v_and_b32_e32 v125, 0xffff0000, v45
	v_add_f32_e32 v116, v116, v124
	v_add_f32_e32 v117, v117, v125
	v_lshlrev_b32_e32 v124, 16, v46
	v_and_b32_e32 v125, 0xffff0000, v46
	v_add_f32_e32 v118, v118, v124
	v_add_f32_e32 v119, v119, v125
	v_lshlrev_b32_e32 v124, 16, v47
	v_and_b32_e32 v125, 0xffff0000, v47
	v_add_f32_e32 v120, v120, v124
	v_add_f32_e32 v121, v121, v125
	s_waitcnt vmcnt(30)
	s_mov_b32 s8, 0xffffff00
	s_mov_b32 s9, 0xffffff00
	s_mov_b64 exec, s[8:9]
	v_lshlrev_b32_e32 v124, 16, v48
	v_and_b32_e32 v125, 0xffff0000, v48
	v_add_f32_e32 v114, v114, v124
	v_add_f32_e32 v115, v115, v125
	v_lshlrev_b32_e32 v124, 16, v49
	v_and_b32_e32 v125, 0xffff0000, v49
	v_add_f32_e32 v116, v116, v124
	v_add_f32_e32 v117, v117, v125
	v_lshlrev_b32_e32 v124, 16, v50
	v_and_b32_e32 v125, 0xffff0000, v50
	v_add_f32_e32 v118, v118, v124
	v_add_f32_e32 v119, v119, v125
	v_lshlrev_b32_e32 v124, 16, v51
	v_and_b32_e32 v125, 0xffff0000, v51
	v_add_f32_e32 v120, v120, v124
	v_add_f32_e32 v121, v121, v125
	v_lshlrev_b32_e32 v124, 16, v52
	v_and_b32_e32 v125, 0xffff0000, v52
	v_add_f32_e32 v114, v114, v124
	v_add_f32_e32 v115, v115, v125
	v_lshlrev_b32_e32 v124, 16, v53
	v_and_b32_e32 v125, 0xffff0000, v53
	v_add_f32_e32 v116, v116, v124
	v_add_f32_e32 v117, v117, v125
	v_lshlrev_b32_e32 v124, 16, v54
	v_and_b32_e32 v125, 0xffff0000, v54
	v_add_f32_e32 v118, v118, v124
	v_add_f32_e32 v119, v119, v125
	v_lshlrev_b32_e32 v124, 16, v55
	v_and_b32_e32 v125, 0xffff0000, v55
	v_add_f32_e32 v120, v120, v124
	v_add_f32_e32 v121, v121, v125
	s_waitcnt vmcnt(24)
	s_mov_b32 s8, 0xffff0000
	s_mov_b32 s9, 0xffff0000
	s_mov_b64 exec, s[8:9]
	v_lshlrev_b32_e32 v124, 16, v56
	v_and_b32_e32 v125, 0xffff0000, v56
	v_add_f32_e32 v114, v114, v124
	v_add_f32_e32 v115, v115, v125
	v_lshlrev_b32_e32 v124, 16, v57
	v_and_b32_e32 v125, 0xffff0000, v57
	v_add_f32_e32 v116, v116, v124
	v_add_f32_e32 v117, v117, v125
	v_lshlrev_b32_e32 v124, 16, v58
	v_and_b32_e32 v125, 0xffff0000, v58
	v_add_f32_e32 v118, v118, v124
	v_add_f32_e32 v119, v119, v125
	v_lshlrev_b32_e32 v124, 16, v59
	v_and_b32_e32 v125, 0xffff0000, v59
	v_add_f32_e32 v120, v120, v124
	v_add_f32_e32 v121, v121, v125
	v_lshlrev_b32_e32 v124, 16, v60
	v_and_b32_e32 v125, 0xffff0000, v60
	v_add_f32_e32 v114, v114, v124
	v_add_f32_e32 v115, v115, v125
	v_lshlrev_b32_e32 v124, 16, v61
	v_and_b32_e32 v125, 0xffff0000, v61
	v_add_f32_e32 v116, v116, v124
	v_add_f32_e32 v117, v117, v125
	v_lshlrev_b32_e32 v124, 16, v62
	v_and_b32_e32 v125, 0xffff0000, v62
	v_add_f32_e32 v118, v118, v124
	v_add_f32_e32 v119, v119, v125
	v_lshlrev_b32_e32 v124, 16, v63
	v_and_b32_e32 v125, 0xffff0000, v63
	v_add_f32_e32 v120, v120, v124
	v_add_f32_e32 v121, v121, v125
	v_lshlrev_b32_e32 v124, 16, v64
	v_and_b32_e32 v125, 0xffff0000, v64
	v_add_f32_e32 v114, v114, v124
	v_add_f32_e32 v115, v115, v125
	v_lshlrev_b32_e32 v124, 16, v65
	v_and_b32_e32 v125, 0xffff0000, v65
	v_add_f32_e32 v116, v116, v124
	v_add_f32_e32 v117, v117, v125
	v_lshlrev_b32_e32 v124, 16, v66
	v_and_b32_e32 v125, 0xffff0000, v66
	v_add_f32_e32 v118, v118, v124
	v_add_f32_e32 v119, v119, v125
	v_lshlrev_b32_e32 v124, 16, v67
	v_and_b32_e32 v125, 0xffff0000, v67
	v_add_f32_e32 v120, v120, v124
	v_add_f32_e32 v121, v121, v125
	v_lshlrev_b32_e32 v124, 16, v68
	v_and_b32_e32 v125, 0xffff0000, v68
	v_add_f32_e32 v114, v114, v124
	v_add_f32_e32 v115, v115, v125
	v_lshlrev_b32_e32 v124, 16, v69
	v_and_b32_e32 v125, 0xffff0000, v69
	v_add_f32_e32 v116, v116, v124
	v_add_f32_e32 v117, v117, v125
	v_lshlrev_b32_e32 v124, 16, v70
	v_and_b32_e32 v125, 0xffff0000, v70
	v_add_f32_e32 v118, v118, v124
	v_add_f32_e32 v119, v119, v125
	v_lshlrev_b32_e32 v124, 16, v71
	v_and_b32_e32 v125, 0xffff0000, v71
	v_add_f32_e32 v120, v120, v124
	v_add_f32_e32 v121, v121, v125
	s_waitcnt vmcnt(12)
	s_mov_b32 s8, 0xff000000
	s_mov_b32 s9, 0xff000000
	s_mov_b64 exec, s[8:9]
	v_lshlrev_b32_e32 v124, 16, v72
	v_and_b32_e32 v125, 0xffff0000, v72
	v_add_f32_e32 v114, v114, v124
	v_add_f32_e32 v115, v115, v125
	v_lshlrev_b32_e32 v124, 16, v73
	v_and_b32_e32 v125, 0xffff0000, v73
	v_add_f32_e32 v116, v116, v124
	v_add_f32_e32 v117, v117, v125
	v_lshlrev_b32_e32 v124, 16, v74
	v_and_b32_e32 v125, 0xffff0000, v74
	v_add_f32_e32 v118, v118, v124
	v_add_f32_e32 v119, v119, v125
	v_lshlrev_b32_e32 v124, 16, v75
	v_and_b32_e32 v125, 0xffff0000, v75
	v_add_f32_e32 v120, v120, v124
	v_add_f32_e32 v121, v121, v125
	v_lshlrev_b32_e32 v124, 16, v76
	v_and_b32_e32 v125, 0xffff0000, v76
	v_add_f32_e32 v114, v114, v124
	v_add_f32_e32 v115, v115, v125
	v_lshlrev_b32_e32 v124, 16, v77
	v_and_b32_e32 v125, 0xffff0000, v77
	v_add_f32_e32 v116, v116, v124
	v_add_f32_e32 v117, v117, v125
	v_lshlrev_b32_e32 v124, 16, v78
	v_and_b32_e32 v125, 0xffff0000, v78
	v_add_f32_e32 v118, v118, v124
	v_add_f32_e32 v119, v119, v125
	v_lshlrev_b32_e32 v124, 16, v79
	v_and_b32_e32 v125, 0xffff0000, v79
	v_add_f32_e32 v120, v120, v124
	v_add_f32_e32 v121, v121, v125
	v_lshlrev_b32_e32 v124, 16, v80
	v_and_b32_e32 v125, 0xffff0000, v80
	v_add_f32_e32 v114, v114, v124
	v_add_f32_e32 v115, v115, v125
	v_lshlrev_b32_e32 v124, 16, v81
	v_and_b32_e32 v125, 0xffff0000, v81
	v_add_f32_e32 v116, v116, v124
	v_add_f32_e32 v117, v117, v125
	v_lshlrev_b32_e32 v124, 16, v82
	v_and_b32_e32 v125, 0xffff0000, v82
	v_add_f32_e32 v118, v118, v124
	v_add_f32_e32 v119, v119, v125
	v_lshlrev_b32_e32 v124, 16, v83
	v_and_b32_e32 v125, 0xffff0000, v83
	v_add_f32_e32 v120, v120, v124
	v_add_f32_e32 v121, v121, v125
	v_lshlrev_b32_e32 v124, 16, v84
	v_and_b32_e32 v125, 0xffff0000, v84
	v_add_f32_e32 v114, v114, v124
	v_add_f32_e32 v115, v115, v125
	v_lshlrev_b32_e32 v124, 16, v85
	v_and_b32_e32 v125, 0xffff0000, v85
	v_add_f32_e32 v116, v116, v124
	v_add_f32_e32 v117, v117, v125
	v_lshlrev_b32_e32 v124, 16, v86
	v_and_b32_e32 v125, 0xffff0000, v86
	v_add_f32_e32 v118, v118, v124
	v_add_f32_e32 v119, v119, v125
	v_lshlrev_b32_e32 v124, 16, v87
	v_and_b32_e32 v125, 0xffff0000, v87
	v_add_f32_e32 v120, v120, v124
	v_add_f32_e32 v121, v121, v125
	v_lshlrev_b32_e32 v124, 16, v88
	v_and_b32_e32 v125, 0xffff0000, v88
	v_add_f32_e32 v114, v114, v124
	v_add_f32_e32 v115, v115, v125
	v_lshlrev_b32_e32 v124, 16, v89
	v_and_b32_e32 v125, 0xffff0000, v89
	v_add_f32_e32 v116, v116, v124
	v_add_f32_e32 v117, v117, v125
	v_lshlrev_b32_e32 v124, 16, v90
	v_and_b32_e32 v125, 0xffff0000, v90
	v_add_f32_e32 v118, v118, v124
	v_add_f32_e32 v119, v119, v125
	v_lshlrev_b32_e32 v124, 16, v91
	v_and_b32_e32 v125, 0xffff0000, v91
	v_add_f32_e32 v120, v120, v124
	v_add_f32_e32 v121, v121, v125
	v_lshlrev_b32_e32 v124, 16, v92
	v_and_b32_e32 v125, 0xffff0000, v92
	v_add_f32_e32 v114, v114, v124
	v_add_f32_e32 v115, v115, v125
	v_lshlrev_b32_e32 v124, 16, v93
	v_and_b32_e32 v125, 0xffff0000, v93
	v_add_f32_e32 v116, v116, v124
	v_add_f32_e32 v117, v117, v125
	v_lshlrev_b32_e32 v124, 16, v94
	v_and_b32_e32 v125, 0xffff0000, v94
	v_add_f32_e32 v118, v118, v124
	v_add_f32_e32 v119, v119, v125
	v_lshlrev_b32_e32 v124, 16, v95
	v_and_b32_e32 v125, 0xffff0000, v95
	v_add_f32_e32 v120, v120, v124
	v_add_f32_e32 v121, v121, v125
	v_lshlrev_b32_e32 v124, 16, v96
	v_and_b32_e32 v125, 0xffff0000, v96
	v_add_f32_e32 v114, v114, v124
	v_add_f32_e32 v115, v115, v125
	v_lshlrev_b32_e32 v124, 16, v97
	v_and_b32_e32 v125, 0xffff0000, v97
	v_add_f32_e32 v116, v116, v124
	v_add_f32_e32 v117, v117, v125
	v_lshlrev_b32_e32 v124, 16, v98
	v_and_b32_e32 v125, 0xffff0000, v98
	v_add_f32_e32 v118, v118, v124
	v_add_f32_e32 v119, v119, v125
	v_lshlrev_b32_e32 v124, 16, v99
	v_and_b32_e32 v125, 0xffff0000, v99
	v_add_f32_e32 v120, v120, v124
	v_add_f32_e32 v121, v121, v125
	v_lshlrev_b32_e32 v124, 16, v100
	v_and_b32_e32 v125, 0xffff0000, v100
	v_add_f32_e32 v114, v114, v124
	v_add_f32_e32 v115, v115, v125
	v_lshlrev_b32_e32 v124, 16, v101
	v_and_b32_e32 v125, 0xffff0000, v101
	v_add_f32_e32 v116, v116, v124
	v_add_f32_e32 v117, v117, v125
	v_lshlrev_b32_e32 v124, 16, v102
	v_and_b32_e32 v125, 0xffff0000, v102
	v_add_f32_e32 v118, v118, v124
	v_add_f32_e32 v119, v119, v125
	v_lshlrev_b32_e32 v124, 16, v103
	v_and_b32_e32 v125, 0xffff0000, v103
	v_add_f32_e32 v120, v120, v124
	v_add_f32_e32 v121, v121, v125
	s_mov_b64 exec, s[10:11]
	s_waitcnt vmcnt(2)
	v_lshlrev_b32_e32 v124, 16, v104
	v_and_b32_e32 v125, 0xffff0000, v104
	v_fma_f32 v114, v123, v114, -v124
	v_fma_f32 v115, v123, v115, -v125
	v_lshlrev_b32_e32 v124, 16, v108
	v_and_b32_e32 v125, 0xffff0000, v108
	v_mul_f32_e32 v114, v114, v124
	v_mul_f32_e32 v115, v115, v125
	v_cvt_pk_bf16_f32 v104, v114, v115
	v_lshlrev_b32_e32 v124, 16, v105
	v_and_b32_e32 v125, 0xffff0000, v105
	v_fma_f32 v116, v123, v116, -v124
	v_fma_f32 v117, v123, v117, -v125
	v_lshlrev_b32_e32 v124, 16, v109
	v_and_b32_e32 v125, 0xffff0000, v109
	v_mul_f32_e32 v116, v116, v124
	v_mul_f32_e32 v117, v117, v125
	v_cvt_pk_bf16_f32 v105, v116, v117
	v_lshlrev_b32_e32 v124, 16, v106
	v_and_b32_e32 v125, 0xffff0000, v106
	v_fma_f32 v118, v123, v118, -v124
	v_fma_f32 v119, v123, v119, -v125
	v_lshlrev_b32_e32 v124, 16, v110
	v_and_b32_e32 v125, 0xffff0000, v110
	v_mul_f32_e32 v118, v118, v124
	v_mul_f32_e32 v119, v119, v125
	v_cvt_pk_bf16_f32 v106, v118, v119
	v_lshlrev_b32_e32 v124, 16, v107
	v_and_b32_e32 v125, 0xffff0000, v107
	v_fma_f32 v120, v123, v120, -v124
	v_fma_f32 v121, v123, v121, -v125
	v_lshlrev_b32_e32 v124, 16, v111
	v_and_b32_e32 v125, 0xffff0000, v111
	v_mul_f32_e32 v120, v120, v124
	v_mul_f32_e32 v121, v121, v125
	v_cvt_pk_bf16_f32 v107, v120, v121
	global_store_dwordx4 v122, v[104:107], s[6:7] offset:3584
	s_waitcnt vmcnt(32)
	v_lshlrev_b32_e32 v124, 16, v128
	v_and_b32_e32 v125, 0xffff0000, v128
	v_add_f32_e32 v216, v216, v124
	v_add_f32_e32 v217, v217, v125
	v_lshlrev_b32_e32 v124, 16, v129
	v_and_b32_e32 v125, 0xffff0000, v129
	v_add_f32_e32 v218, v218, v124
	v_add_f32_e32 v219, v219, v125
	v_lshlrev_b32_e32 v124, 16, v130
	v_and_b32_e32 v125, 0xffff0000, v130
	v_add_f32_e32 v220, v220, v124
	v_add_f32_e32 v221, v221, v125
	v_lshlrev_b32_e32 v124, 16, v131
	v_and_b32_e32 v125, 0xffff0000, v131
	v_add_f32_e32 v222, v222, v124
	v_add_f32_e32 v223, v223, v125
	v_lshlrev_b32_e32 v124, 16, v132
	v_and_b32_e32 v125, 0xffff0000, v132
	v_add_f32_e32 v216, v216, v124
	v_add_f32_e32 v217, v217, v125
	v_lshlrev_b32_e32 v124, 16, v133
	v_and_b32_e32 v125, 0xffff0000, v133
	v_add_f32_e32 v218, v218, v124
	v_add_f32_e32 v219, v219, v125
	v_lshlrev_b32_e32 v124, 16, v134
	v_and_b32_e32 v125, 0xffff0000, v134
	v_add_f32_e32 v220, v220, v124
	v_add_f32_e32 v221, v221, v125
	v_lshlrev_b32_e32 v124, 16, v135
	v_and_b32_e32 v125, 0xffff0000, v135
	v_add_f32_e32 v222, v222, v124
	v_add_f32_e32 v223, v223, v125
	s_waitcnt vmcnt(28)
	s_mov_b32 s8, 0xffffff00
	s_mov_b32 s9, 0xffffff00
	s_mov_b64 exec, s[8:9]
	v_lshlrev_b32_e32 v124, 16, v136
	v_and_b32_e32 v125, 0xffff0000, v136
	v_add_f32_e32 v216, v216, v124
	v_add_f32_e32 v217, v217, v125
	v_lshlrev_b32_e32 v124, 16, v137
	v_and_b32_e32 v125, 0xffff0000, v137
	v_add_f32_e32 v218, v218, v124
	v_add_f32_e32 v219, v219, v125
	v_lshlrev_b32_e32 v124, 16, v138
	v_and_b32_e32 v125, 0xffff0000, v138
	v_add_f32_e32 v220, v220, v124
	v_add_f32_e32 v221, v221, v125
	v_lshlrev_b32_e32 v124, 16, v139
	v_and_b32_e32 v125, 0xffff0000, v139
	v_add_f32_e32 v222, v222, v124
	v_add_f32_e32 v223, v223, v125
	v_lshlrev_b32_e32 v124, 16, v140
	v_and_b32_e32 v125, 0xffff0000, v140
	v_add_f32_e32 v216, v216, v124
	v_add_f32_e32 v217, v217, v125
	v_lshlrev_b32_e32 v124, 16, v141
	v_and_b32_e32 v125, 0xffff0000, v141
	v_add_f32_e32 v218, v218, v124
	v_add_f32_e32 v219, v219, v125
	v_lshlrev_b32_e32 v124, 16, v142
	v_and_b32_e32 v125, 0xffff0000, v142
	v_add_f32_e32 v220, v220, v124
	v_add_f32_e32 v221, v221, v125
	v_lshlrev_b32_e32 v124, 16, v143
	v_and_b32_e32 v125, 0xffff0000, v143
	v_add_f32_e32 v222, v222, v124
	v_add_f32_e32 v223, v223, v125
	s_waitcnt vmcnt(20)
	s_mov_b32 s8, 0xffff0000
	s_mov_b32 s9, 0xffff0000
	s_mov_b64 exec, s[8:9]
	v_lshlrev_b32_e32 v124, 16, v144
	v_and_b32_e32 v125, 0xffff0000, v144
	v_add_f32_e32 v216, v216, v124
	v_add_f32_e32 v217, v217, v125
	v_lshlrev_b32_e32 v124, 16, v145
	v_and_b32_e32 v125, 0xffff0000, v145
	v_add_f32_e32 v218, v218, v124
	v_add_f32_e32 v219, v219, v125
	v_lshlrev_b32_e32 v124, 16, v146
	v_and_b32_e32 v125, 0xffff0000, v146
	v_add_f32_e32 v220, v220, v124
	v_add_f32_e32 v221, v221, v125
	v_lshlrev_b32_e32 v124, 16, v147
	v_and_b32_e32 v125, 0xffff0000, v147
	v_add_f32_e32 v222, v222, v124
	v_add_f32_e32 v223, v223, v125
	v_lshlrev_b32_e32 v124, 16, v148
	v_and_b32_e32 v125, 0xffff0000, v148
	v_add_f32_e32 v216, v216, v124
	v_add_f32_e32 v217, v217, v125
	v_lshlrev_b32_e32 v124, 16, v149
	v_and_b32_e32 v125, 0xffff0000, v149
	v_add_f32_e32 v218, v218, v124
	v_add_f32_e32 v219, v219, v125
	v_lshlrev_b32_e32 v124, 16, v150
	v_and_b32_e32 v125, 0xffff0000, v150
	v_add_f32_e32 v220, v220, v124
	v_add_f32_e32 v221, v221, v125
	v_lshlrev_b32_e32 v124, 16, v151
	v_and_b32_e32 v125, 0xffff0000, v151
	v_add_f32_e32 v222, v222, v124
	v_add_f32_e32 v223, v223, v125
	v_lshlrev_b32_e32 v124, 16, v152
	v_and_b32_e32 v125, 0xffff0000, v152
	v_add_f32_e32 v216, v216, v124
	v_add_f32_e32 v217, v217, v125
	v_lshlrev_b32_e32 v124, 16, v153
	v_and_b32_e32 v125, 0xffff0000, v153
	v_add_f32_e32 v218, v218, v124
	v_add_f32_e32 v219, v219, v125
	v_lshlrev_b32_e32 v124, 16, v154
	v_and_b32_e32 v125, 0xffff0000, v154
	v_add_f32_e32 v220, v220, v124
	v_add_f32_e32 v221, v221, v125
	v_lshlrev_b32_e32 v124, 16, v155
	v_and_b32_e32 v125, 0xffff0000, v155
	v_add_f32_e32 v222, v222, v124
	v_add_f32_e32 v223, v223, v125
	v_lshlrev_b32_e32 v124, 16, v156
	v_and_b32_e32 v125, 0xffff0000, v156
	v_add_f32_e32 v216, v216, v124
	v_add_f32_e32 v217, v217, v125
	v_lshlrev_b32_e32 v124, 16, v157
	v_and_b32_e32 v125, 0xffff0000, v157
	v_add_f32_e32 v218, v218, v124
	v_add_f32_e32 v219, v219, v125
	v_lshlrev_b32_e32 v124, 16, v158
	v_and_b32_e32 v125, 0xffff0000, v158
	v_add_f32_e32 v220, v220, v124
	v_add_f32_e32 v221, v221, v125
	v_lshlrev_b32_e32 v124, 16, v159
	v_and_b32_e32 v125, 0xffff0000, v159
	v_add_f32_e32 v222, v222, v124
	v_add_f32_e32 v223, v223, v125
	s_waitcnt vmcnt(4)
	s_mov_b32 s8, 0xff000000
	s_mov_b32 s9, 0xff000000
	s_mov_b64 exec, s[8:9]
	v_lshlrev_b32_e32 v124, 16, v160
	v_and_b32_e32 v125, 0xffff0000, v160
	v_add_f32_e32 v216, v216, v124
	v_add_f32_e32 v217, v217, v125
	v_lshlrev_b32_e32 v124, 16, v161
	v_and_b32_e32 v125, 0xffff0000, v161
	v_add_f32_e32 v218, v218, v124
	v_add_f32_e32 v219, v219, v125
	v_lshlrev_b32_e32 v124, 16, v162
	v_and_b32_e32 v125, 0xffff0000, v162
	v_add_f32_e32 v220, v220, v124
	v_add_f32_e32 v221, v221, v125
	v_lshlrev_b32_e32 v124, 16, v163
	v_and_b32_e32 v125, 0xffff0000, v163
	v_add_f32_e32 v222, v222, v124
	v_add_f32_e32 v223, v223, v125
	v_lshlrev_b32_e32 v124, 16, v164
	v_and_b32_e32 v125, 0xffff0000, v164
	v_add_f32_e32 v216, v216, v124
	v_add_f32_e32 v217, v217, v125
	v_lshlrev_b32_e32 v124, 16, v165
	v_and_b32_e32 v125, 0xffff0000, v165
	v_add_f32_e32 v218, v218, v124
	v_add_f32_e32 v219, v219, v125
	v_lshlrev_b32_e32 v124, 16, v166
	v_and_b32_e32 v125, 0xffff0000, v166
	v_add_f32_e32 v220, v220, v124
	v_add_f32_e32 v221, v221, v125
	v_lshlrev_b32_e32 v124, 16, v167
	v_and_b32_e32 v125, 0xffff0000, v167
	v_add_f32_e32 v222, v222, v124
	v_add_f32_e32 v223, v223, v125
	v_lshlrev_b32_e32 v124, 16, v172
	v_and_b32_e32 v125, 0xffff0000, v172
	v_add_f32_e32 v216, v216, v124
	v_add_f32_e32 v217, v217, v125
	v_lshlrev_b32_e32 v124, 16, v173
	v_and_b32_e32 v125, 0xffff0000, v173
	v_add_f32_e32 v218, v218, v124
	v_add_f32_e32 v219, v219, v125
	v_lshlrev_b32_e32 v124, 16, v174
	v_and_b32_e32 v125, 0xffff0000, v174
	v_add_f32_e32 v220, v220, v124
	v_add_f32_e32 v221, v221, v125
	v_lshlrev_b32_e32 v124, 16, v175
	v_and_b32_e32 v125, 0xffff0000, v175
	v_add_f32_e32 v222, v222, v124
	v_add_f32_e32 v223, v223, v125
	v_lshlrev_b32_e32 v124, 16, v176
	v_and_b32_e32 v125, 0xffff0000, v176
	v_add_f32_e32 v216, v216, v124
	v_add_f32_e32 v217, v217, v125
	v_lshlrev_b32_e32 v124, 16, v177
	v_and_b32_e32 v125, 0xffff0000, v177
	v_add_f32_e32 v218, v218, v124
	v_add_f32_e32 v219, v219, v125
	v_lshlrev_b32_e32 v124, 16, v178
	v_and_b32_e32 v125, 0xffff0000, v178
	v_add_f32_e32 v220, v220, v124
	v_add_f32_e32 v221, v221, v125
	v_lshlrev_b32_e32 v124, 16, v179
	v_and_b32_e32 v125, 0xffff0000, v179
	v_add_f32_e32 v222, v222, v124
	v_add_f32_e32 v223, v223, v125
	v_lshlrev_b32_e32 v124, 16, v180
	v_and_b32_e32 v125, 0xffff0000, v180
	v_add_f32_e32 v216, v216, v124
	v_add_f32_e32 v217, v217, v125
	v_lshlrev_b32_e32 v124, 16, v181
	v_and_b32_e32 v125, 0xffff0000, v181
	v_add_f32_e32 v218, v218, v124
	v_add_f32_e32 v219, v219, v125
	v_lshlrev_b32_e32 v124, 16, v182
	v_and_b32_e32 v125, 0xffff0000, v182
	v_add_f32_e32 v220, v220, v124
	v_add_f32_e32 v221, v221, v125
	v_lshlrev_b32_e32 v124, 16, v183
	v_and_b32_e32 v125, 0xffff0000, v183
	v_add_f32_e32 v222, v222, v124
	v_add_f32_e32 v223, v223, v125
	v_lshlrev_b32_e32 v124, 16, v184
	v_and_b32_e32 v125, 0xffff0000, v184
	v_add_f32_e32 v216, v216, v124
	v_add_f32_e32 v217, v217, v125
	v_lshlrev_b32_e32 v124, 16, v185
	v_and_b32_e32 v125, 0xffff0000, v185
	v_add_f32_e32 v218, v218, v124
	v_add_f32_e32 v219, v219, v125
	v_lshlrev_b32_e32 v124, 16, v186
	v_and_b32_e32 v125, 0xffff0000, v186
	v_add_f32_e32 v220, v220, v124
	v_add_f32_e32 v221, v221, v125
	v_lshlrev_b32_e32 v124, 16, v187
	v_and_b32_e32 v125, 0xffff0000, v187
	v_add_f32_e32 v222, v222, v124
	v_add_f32_e32 v223, v223, v125
	v_lshlrev_b32_e32 v124, 16, v188
	v_and_b32_e32 v125, 0xffff0000, v188
	v_add_f32_e32 v216, v216, v124
	v_add_f32_e32 v217, v217, v125
	v_lshlrev_b32_e32 v124, 16, v189
	v_and_b32_e32 v125, 0xffff0000, v189
	v_add_f32_e32 v218, v218, v124
	v_add_f32_e32 v219, v219, v125
	v_lshlrev_b32_e32 v124, 16, v190
	v_and_b32_e32 v125, 0xffff0000, v190
	v_add_f32_e32 v220, v220, v124
	v_add_f32_e32 v221, v221, v125
	v_lshlrev_b32_e32 v124, 16, v191
	v_and_b32_e32 v125, 0xffff0000, v191
	v_add_f32_e32 v222, v222, v124
	v_add_f32_e32 v223, v223, v125
	v_lshlrev_b32_e32 v124, 16, v192
	v_and_b32_e32 v125, 0xffff0000, v192
	v_add_f32_e32 v216, v216, v124
	v_add_f32_e32 v217, v217, v125
	v_lshlrev_b32_e32 v124, 16, v193
	v_and_b32_e32 v125, 0xffff0000, v193
	v_add_f32_e32 v218, v218, v124
	v_add_f32_e32 v219, v219, v125
	v_lshlrev_b32_e32 v124, 16, v194
	v_and_b32_e32 v125, 0xffff0000, v194
	v_add_f32_e32 v220, v220, v124
	v_add_f32_e32 v221, v221, v125
	v_lshlrev_b32_e32 v124, 16, v195
	v_and_b32_e32 v125, 0xffff0000, v195
	v_add_f32_e32 v222, v222, v124
	v_add_f32_e32 v223, v223, v125
	s_mov_b64 exec, s[10:11]
	s_waitcnt vmcnt(0)
	v_lshlrev_b32_e32 v124, 16, v208
	v_and_b32_e32 v125, 0xffff0000, v208
	v_fma_f32 v216, v123, v216, -v124
	v_fma_f32 v217, v123, v217, -v125
	v_lshlrev_b32_e32 v124, 16, v212
	v_and_b32_e32 v125, 0xffff0000, v212
	v_mul_f32_e32 v216, v216, v124
	v_mul_f32_e32 v217, v217, v125
	v_cvt_pk_bf16_f32 v208, v216, v217
	v_lshlrev_b32_e32 v124, 16, v209
	v_and_b32_e32 v125, 0xffff0000, v209
	v_fma_f32 v218, v123, v218, -v124
	v_fma_f32 v219, v123, v219, -v125
	v_lshlrev_b32_e32 v124, 16, v213
	v_and_b32_e32 v125, 0xffff0000, v213
	v_mul_f32_e32 v218, v218, v124
	v_mul_f32_e32 v219, v219, v125
	v_cvt_pk_bf16_f32 v209, v218, v219
	v_lshlrev_b32_e32 v124, 16, v210
	v_and_b32_e32 v125, 0xffff0000, v210
	v_fma_f32 v220, v123, v220, -v124
	v_fma_f32 v221, v123, v221, -v125
	v_lshlrev_b32_e32 v124, 16, v214
	v_and_b32_e32 v125, 0xffff0000, v214
	v_mul_f32_e32 v220, v220, v124
	v_mul_f32_e32 v221, v221, v125
	v_cvt_pk_bf16_f32 v210, v220, v221
	v_lshlrev_b32_e32 v124, 16, v211
	v_and_b32_e32 v125, 0xffff0000, v211
	v_fma_f32 v222, v123, v222, -v124
	v_fma_f32 v223, v123, v223, -v125
	v_lshlrev_b32_e32 v124, 16, v215
	v_and_b32_e32 v125, 0xffff0000, v215
	v_mul_f32_e32 v222, v222, v124
	v_mul_f32_e32 v223, v223, v125
	v_cvt_pk_bf16_f32 v211, v222, v223
	global_store_dwordx4 v122, v[208:211], s[42:43] offset:3584
	v_add_u32_e32 v14, s0, v14
	s_branch .Lpool_next
.Lpool_single:
	global_load_dwordx4 v[40:43], v112, s[6:7]
	v_add_u32_e32 v113, 0x1800, v112
	global_load_dwordx4 v[44:47], v113, s[6:7]
	s_mov_b64 s[10:11], exec
	s_mov_b32 s8, 0xffffff00
	s_mov_b32 s9, 0xffffff00
	s_mov_b64 exec, s[8:9]
	v_add_u32_e32 v113, 0x3000, v112
	global_load_dwordx4 v[48:51], v113, s[6:7]
	v_add_u32_e32 v113, 0x4800, v112
	global_load_dwordx4 v[52:55], v113, s[6:7]
	s_mov_b32 s8, 0xffff0000
	s_mov_b32 s9, 0xffff0000
	s_mov_b64 exec, s[8:9]
	v_add_u32_e32 v113, 0x6000, v112
	global_load_dwordx4 v[56:59], v113, s[6:7]
	v_add_u32_e32 v113, 0x7800, v112
	global_load_dwordx4 v[60:63], v113, s[6:7]
	v_add_u32_e32 v113, 0x9000, v112
	global_load_dwordx4 v[64:67], v113, s[6:7]
	v_add_u32_e32 v113, 0xa800, v112
	global_load_dwordx4 v[68:71], v113, s[6:7]
	s_mov_b32 s8, 0xff000000
	s_mov_b32 s9, 0xff000000
	s_mov_b64 exec, s[8:9]
	v_add_u32_e32 v113, 0xc000, v112
	global_load_dwordx4 v[72:75], v113, s[6:7]
	v_add_u32_e32 v113, 0xd800, v112
	global_load_dwordx4 v[76:79], v113, s[6:7]
	v_add_u32_e32 v113, 0xf000, v112
	global_load_dwordx4 v[80:83], v113, s[6:7]
	v_add_u32_e32 v113, 0x10800, v112
	global_load_dwordx4 v[84:87], v113, s[6:7]
	v_add_u32_e32 v113, 0x12000, v112
	global_load_dwordx4 v[88:91], v113, s[6:7]
	v_add_u32_e32 v113, 0x13800, v112
	global_load_dwordx4 v[92:95], v113, s[6:7]
	v_add_u32_e32 v113, 0x15000, v112
	global_load_dwordx4 v[96:99], v113, s[6:7]
	v_add_u32_e32 v113, 0x16800, v112
	global_load_dwordx4 v[100:103], v113, s[6:7]
	s_mov_b64 exec, s[10:11]
	global_load_dwordx4 v[104:107], v122, s[6:7]
	global_load_dwordx4 v[108:111], v122, s[6:7] offset:3584
	v_mov_b32_e32 v114, 0
	v_mov_b32_e32 v115, 0
	v_mov_b32_e32 v116, 0
	v_mov_b32_e32 v117, 0
	v_mov_b32_e32 v118, 0
	v_mov_b32_e32 v119, 0
	v_mov_b32_e32 v120, 0
	v_mov_b32_e32 v121, 0
	v_bfe_u32 v123, v207, 3, 2
	v_sub_u32_e32 v123, 0x7e, v123
	v_lshlrev_b32_e32 v123, 23, v123
	s_waitcnt vmcnt(16)
	v_lshlrev_b32_e32 v124, 16, v40
	v_and_b32_e32 v125, 0xffff0000, v40
	v_add_f32_e32 v114, v114, v124
	v_add_f32_e32 v115, v115, v125
	v_lshlrev_b32_e32 v124, 16, v41
	v_and_b32_e32 v125, 0xffff0000, v41
	v_add_f32_e32 v116, v116, v124
	v_add_f32_e32 v117, v117, v125
	v_lshlrev_b32_e32 v124, 16, v42
	v_and_b32_e32 v125, 0xffff0000, v42
	v_add_f32_e32 v118, v118, v124
	v_add_f32_e32 v119, v119, v125
	v_lshlrev_b32_e32 v124, 16, v43
	v_and_b32_e32 v125, 0xffff0000, v43
	v_add_f32_e32 v120, v120, v124
	v_add_f32_e32 v121, v121, v125
	v_lshlrev_b32_e32 v124, 16, v44
	v_and_b32_e32 v125, 0xffff0000, v44
	v_add_f32_e32 v114, v114, v124
	v_add_f32_e32 v115, v115, v125
	v_lshlrev_b32_e32 v124, 16, v45
	v_and_b32_e32 v125, 0xffff0000, v45
	v_add_f32_e32 v116, v116, v124
	v_add_f32_e32 v117, v117, v125
	v_lshlrev_b32_e32 v124, 16, v46
	v_and_b32_e32 v125, 0xffff0000, v46
	v_add_f32_e32 v118, v118, v124
	v_add_f32_e32 v119, v119, v125
	v_lshlrev_b32_e32 v124, 16, v47
	v_and_b32_e32 v125, 0xffff0000, v47
	v_add_f32_e32 v120, v120, v124
	v_add_f32_e32 v121, v121, v125
	s_waitcnt vmcnt(14)
	s_mov_b32 s8, 0xffffff00
	s_mov_b32 s9, 0xffffff00
	s_mov_b64 exec, s[8:9]
	v_lshlrev_b32_e32 v124, 16, v48
	v_and_b32_e32 v125, 0xffff0000, v48
	v_add_f32_e32 v114, v114, v124
	v_add_f32_e32 v115, v115, v125
	v_lshlrev_b32_e32 v124, 16, v49
	v_and_b32_e32 v125, 0xffff0000, v49
	v_add_f32_e32 v116, v116, v124
	v_add_f32_e32 v117, v117, v125
	v_lshlrev_b32_e32 v124, 16, v50
	v_and_b32_e32 v125, 0xffff0000, v50
	v_add_f32_e32 v118, v118, v124
	v_add_f32_e32 v119, v119, v125
	v_lshlrev_b32_e32 v124, 16, v51
	v_and_b32_e32 v125, 0xffff0000, v51
	v_add_f32_e32 v120, v120, v124
	v_add_f32_e32 v121, v121, v125
	v_lshlrev_b32_e32 v124, 16, v52
	v_and_b32_e32 v125, 0xffff0000, v52
	v_add_f32_e32 v114, v114, v124
	v_add_f32_e32 v115, v115, v125
	v_lshlrev_b32_e32 v124, 16, v53
	v_and_b32_e32 v125, 0xffff0000, v53
	v_add_f32_e32 v116, v116, v124
	v_add_f32_e32 v117, v117, v125
	v_lshlrev_b32_e32 v124, 16, v54
	v_and_b32_e32 v125, 0xffff0000, v54
	v_add_f32_e32 v118, v118, v124
	v_add_f32_e32 v119, v119, v125
	v_lshlrev_b32_e32 v124, 16, v55
	v_and_b32_e32 v125, 0xffff0000, v55
	v_add_f32_e32 v120, v120, v124
	v_add_f32_e32 v121, v121, v125
	s_waitcnt vmcnt(10)
	s_mov_b32 s8, 0xffff0000
	s_mov_b32 s9, 0xffff0000
	s_mov_b64 exec, s[8:9]
	v_lshlrev_b32_e32 v124, 16, v56
	v_and_b32_e32 v125, 0xffff0000, v56
	v_add_f32_e32 v114, v114, v124
	v_add_f32_e32 v115, v115, v125
	v_lshlrev_b32_e32 v124, 16, v57
	v_and_b32_e32 v125, 0xffff0000, v57
	v_add_f32_e32 v116, v116, v124
	v_add_f32_e32 v117, v117, v125
	v_lshlrev_b32_e32 v124, 16, v58
	v_and_b32_e32 v125, 0xffff0000, v58
	v_add_f32_e32 v118, v118, v124
	v_add_f32_e32 v119, v119, v125
	v_lshlrev_b32_e32 v124, 16, v59
	v_and_b32_e32 v125, 0xffff0000, v59
	v_add_f32_e32 v120, v120, v124
	v_add_f32_e32 v121, v121, v125
	v_lshlrev_b32_e32 v124, 16, v60
	v_and_b32_e32 v125, 0xffff0000, v60
	v_add_f32_e32 v114, v114, v124
	v_add_f32_e32 v115, v115, v125
	v_lshlrev_b32_e32 v124, 16, v61
	v_and_b32_e32 v125, 0xffff0000, v61
	v_add_f32_e32 v116, v116, v124
	v_add_f32_e32 v117, v117, v125
	v_lshlrev_b32_e32 v124, 16, v62
	v_and_b32_e32 v125, 0xffff0000, v62
	v_add_f32_e32 v118, v118, v124
	v_add_f32_e32 v119, v119, v125
	v_lshlrev_b32_e32 v124, 16, v63
	v_and_b32_e32 v125, 0xffff0000, v63
	v_add_f32_e32 v120, v120, v124
	v_add_f32_e32 v121, v121, v125
	v_lshlrev_b32_e32 v124, 16, v64
	v_and_b32_e32 v125, 0xffff0000, v64
	v_add_f32_e32 v114, v114, v124
	v_add_f32_e32 v115, v115, v125
	v_lshlrev_b32_e32 v124, 16, v65
	v_and_b32_e32 v125, 0xffff0000, v65
	v_add_f32_e32 v116, v116, v124
	v_add_f32_e32 v117, v117, v125
	v_lshlrev_b32_e32 v124, 16, v66
	v_and_b32_e32 v125, 0xffff0000, v66
	v_add_f32_e32 v118, v118, v124
	v_add_f32_e32 v119, v119, v125
	v_lshlrev_b32_e32 v124, 16, v67
	v_and_b32_e32 v125, 0xffff0000, v67
	v_add_f32_e32 v120, v120, v124
	v_add_f32_e32 v121, v121, v125
	v_lshlrev_b32_e32 v124, 16, v68
	v_and_b32_e32 v125, 0xffff0000, v68
	v_add_f32_e32 v114, v114, v124
	v_add_f32_e32 v115, v115, v125
	v_lshlrev_b32_e32 v124, 16, v69
	v_and_b32_e32 v125, 0xffff0000, v69
	v_add_f32_e32 v116, v116, v124
	v_add_f32_e32 v117, v117, v125
	v_lshlrev_b32_e32 v124, 16, v70
	v_and_b32_e32 v125, 0xffff0000, v70
	v_add_f32_e32 v118, v118, v124
	v_add_f32_e32 v119, v119, v125
	v_lshlrev_b32_e32 v124, 16, v71
	v_and_b32_e32 v125, 0xffff0000, v71
	v_add_f32_e32 v120, v120, v124
	v_add_f32_e32 v121, v121, v125
	s_waitcnt vmcnt(2)
	s_mov_b32 s8, 0xff000000
	s_mov_b32 s9, 0xff000000
	s_mov_b64 exec, s[8:9]
	v_lshlrev_b32_e32 v124, 16, v72
	v_and_b32_e32 v125, 0xffff0000, v72
	v_add_f32_e32 v114, v114, v124
	v_add_f32_e32 v115, v115, v125
	v_lshlrev_b32_e32 v124, 16, v73
	v_and_b32_e32 v125, 0xffff0000, v73
	v_add_f32_e32 v116, v116, v124
	v_add_f32_e32 v117, v117, v125
	v_lshlrev_b32_e32 v124, 16, v74
	v_and_b32_e32 v125, 0xffff0000, v74
	v_add_f32_e32 v118, v118, v124
	v_add_f32_e32 v119, v119, v125
	v_lshlrev_b32_e32 v124, 16, v75
	v_and_b32_e32 v125, 0xffff0000, v75
	v_add_f32_e32 v120, v120, v124
	v_add_f32_e32 v121, v121, v125
	v_lshlrev_b32_e32 v124, 16, v76
	v_and_b32_e32 v125, 0xffff0000, v76
	v_add_f32_e32 v114, v114, v124
	v_add_f32_e32 v115, v115, v125
	v_lshlrev_b32_e32 v124, 16, v77
	v_and_b32_e32 v125, 0xffff0000, v77
	v_add_f32_e32 v116, v116, v124
	v_add_f32_e32 v117, v117, v125
	v_lshlrev_b32_e32 v124, 16, v78
	v_and_b32_e32 v125, 0xffff0000, v78
	v_add_f32_e32 v118, v118, v124
	v_add_f32_e32 v119, v119, v125
	v_lshlrev_b32_e32 v124, 16, v79
	v_and_b32_e32 v125, 0xffff0000, v79
	v_add_f32_e32 v120, v120, v124
	v_add_f32_e32 v121, v121, v125
	v_lshlrev_b32_e32 v124, 16, v80
	v_and_b32_e32 v125, 0xffff0000, v80
	v_add_f32_e32 v114, v114, v124
	v_add_f32_e32 v115, v115, v125
	v_lshlrev_b32_e32 v124, 16, v81
	v_and_b32_e32 v125, 0xffff0000, v81
	v_add_f32_e32 v116, v116, v124
	v_add_f32_e32 v117, v117, v125
	v_lshlrev_b32_e32 v124, 16, v82
	v_and_b32_e32 v125, 0xffff0000, v82
	v_add_f32_e32 v118, v118, v124
	v_add_f32_e32 v119, v119, v125
	v_lshlrev_b32_e32 v124, 16, v83
	v_and_b32_e32 v125, 0xffff0000, v83
	v_add_f32_e32 v120, v120, v124
	v_add_f32_e32 v121, v121, v125
	v_lshlrev_b32_e32 v124, 16, v84
	v_and_b32_e32 v125, 0xffff0000, v84
	v_add_f32_e32 v114, v114, v124
	v_add_f32_e32 v115, v115, v125
	v_lshlrev_b32_e32 v124, 16, v85
	v_and_b32_e32 v125, 0xffff0000, v85
	v_add_f32_e32 v116, v116, v124
	v_add_f32_e32 v117, v117, v125
	v_lshlrev_b32_e32 v124, 16, v86
	v_and_b32_e32 v125, 0xffff0000, v86
	v_add_f32_e32 v118, v118, v124
	v_add_f32_e32 v119, v119, v125
	v_lshlrev_b32_e32 v124, 16, v87
	v_and_b32_e32 v125, 0xffff0000, v87
	v_add_f32_e32 v120, v120, v124
	v_add_f32_e32 v121, v121, v125
	v_lshlrev_b32_e32 v124, 16, v88
	v_and_b32_e32 v125, 0xffff0000, v88
	v_add_f32_e32 v114, v114, v124
	v_add_f32_e32 v115, v115, v125
	v_lshlrev_b32_e32 v124, 16, v89
	v_and_b32_e32 v125, 0xffff0000, v89
	v_add_f32_e32 v116, v116, v124
	v_add_f32_e32 v117, v117, v125
	v_lshlrev_b32_e32 v124, 16, v90
	v_and_b32_e32 v125, 0xffff0000, v90
	v_add_f32_e32 v118, v118, v124
	v_add_f32_e32 v119, v119, v125
	v_lshlrev_b32_e32 v124, 16, v91
	v_and_b32_e32 v125, 0xffff0000, v91
	v_add_f32_e32 v120, v120, v124
	v_add_f32_e32 v121, v121, v125
	v_lshlrev_b32_e32 v124, 16, v92
	v_and_b32_e32 v125, 0xffff0000, v92
	v_add_f32_e32 v114, v114, v124
	v_add_f32_e32 v115, v115, v125
	v_lshlrev_b32_e32 v124, 16, v93
	v_and_b32_e32 v125, 0xffff0000, v93
	v_add_f32_e32 v116, v116, v124
	v_add_f32_e32 v117, v117, v125
	v_lshlrev_b32_e32 v124, 16, v94
	v_and_b32_e32 v125, 0xffff0000, v94
	v_add_f32_e32 v118, v118, v124
	v_add_f32_e32 v119, v119, v125
	v_lshlrev_b32_e32 v124, 16, v95
	v_and_b32_e32 v125, 0xffff0000, v95
	v_add_f32_e32 v120, v120, v124
	v_add_f32_e32 v121, v121, v125
	v_lshlrev_b32_e32 v124, 16, v96
	v_and_b32_e32 v125, 0xffff0000, v96
	v_add_f32_e32 v114, v114, v124
	v_add_f32_e32 v115, v115, v125
	v_lshlrev_b32_e32 v124, 16, v97
	v_and_b32_e32 v125, 0xffff0000, v97
	v_add_f32_e32 v116, v116, v124
	v_add_f32_e32 v117, v117, v125
	v_lshlrev_b32_e32 v124, 16, v98
	v_and_b32_e32 v125, 0xffff0000, v98
	v_add_f32_e32 v118, v118, v124
	v_add_f32_e32 v119, v119, v125
	v_lshlrev_b32_e32 v124, 16, v99
	v_and_b32_e32 v125, 0xffff0000, v99
	v_add_f32_e32 v120, v120, v124
	v_add_f32_e32 v121, v121, v125
	v_lshlrev_b32_e32 v124, 16, v100
	v_and_b32_e32 v125, 0xffff0000, v100
	v_add_f32_e32 v114, v114, v124
	v_add_f32_e32 v115, v115, v125
	v_lshlrev_b32_e32 v124, 16, v101
	v_and_b32_e32 v125, 0xffff0000, v101
	v_add_f32_e32 v116, v116, v124
	v_add_f32_e32 v117, v117, v125
	v_lshlrev_b32_e32 v124, 16, v102
	v_and_b32_e32 v125, 0xffff0000, v102
	v_add_f32_e32 v118, v118, v124
	v_add_f32_e32 v119, v119, v125
	v_lshlrev_b32_e32 v124, 16, v103
	v_and_b32_e32 v125, 0xffff0000, v103
	v_add_f32_e32 v120, v120, v124
	v_add_f32_e32 v121, v121, v125
	s_mov_b64 exec, s[10:11]
	s_waitcnt vmcnt(0)
	v_lshlrev_b32_e32 v124, 16, v104
	v_and_b32_e32 v125, 0xffff0000, v104
	v_fma_f32 v114, v123, v114, -v124
	v_fma_f32 v115, v123, v115, -v125
	v_lshlrev_b32_e32 v124, 16, v108
	v_and_b32_e32 v125, 0xffff0000, v108
	v_mul_f32_e32 v114, v114, v124
	v_mul_f32_e32 v115, v115, v125
	v_cvt_pk_bf16_f32 v104, v114, v115
	v_lshlrev_b32_e32 v124, 16, v105
	v_and_b32_e32 v125, 0xffff0000, v105
	v_fma_f32 v116, v123, v116, -v124
	v_fma_f32 v117, v123, v117, -v125
	v_lshlrev_b32_e32 v124, 16, v109
	v_and_b32_e32 v125, 0xffff0000, v109
	v_mul_f32_e32 v116, v116, v124
	v_mul_f32_e32 v117, v117, v125
	v_cvt_pk_bf16_f32 v105, v116, v117
	v_lshlrev_b32_e32 v124, 16, v106
	v_and_b32_e32 v125, 0xffff0000, v106
	v_fma_f32 v118, v123, v118, -v124
	v_fma_f32 v119, v123, v119, -v125
	v_lshlrev_b32_e32 v124, 16, v110
	v_and_b32_e32 v125, 0xffff0000, v110
	v_mul_f32_e32 v118, v118, v124
	v_mul_f32_e32 v119, v119, v125
	v_cvt_pk_bf16_f32 v106, v118, v119
	v_lshlrev_b32_e32 v124, 16, v107
	v_and_b32_e32 v125, 0xffff0000, v107
	v_fma_f32 v120, v123, v120, -v124
	v_fma_f32 v121, v123, v121, -v125
	v_lshlrev_b32_e32 v124, 16, v111
	v_and_b32_e32 v125, 0xffff0000, v111
	v_mul_f32_e32 v120, v120, v124
	v_mul_f32_e32 v121, v121, v125
	v_cvt_pk_bf16_f32 v107, v120, v121
	global_store_dwordx4 v122, v[104:107], s[6:7] offset:3584
.Lpool_next:
	v_add_u32_e32 v14, s0, v14
	v_cmp_lt_i32_e32 vcc, s21, v14
	s_or_b64 s[40:41], vcc, s[40:41]
	s_andn2_b64 exec, exec, s[40:41]
	s_cbranch_execz .LBB0_306
	s_branch .LBB0_302
